# SSDOUT layer1: remap the 32 third-round ssd_out items onto the 32 virtual blocks whose first item is a skipped ctx chunk (2 rounds instead of 3)
# speedup vs baseline: 1.0164x; 1.0164x over previous
.LBB0_2185:
	s_add_i32 s3, s3, s33
	s_cmpk_lt_i32 s3, 0x400
	s_cbranch_scc1 .LBB0_2186
	s_cmpk_lg_i32 s33, 0x200
	s_cbranch_scc1 .Lssd1_orig
	s_bitcmp0_b32 s3, 4
	s_cbranch_scc1 .Lssd1_orig
	s_sub_i32 s2, s3, 0x400
	s_cmpk_lt_i32 s2, 64
	s_cbranch_scc1 .LBB0_2711
	s_sub_i32 s2, s2, 0x100
	s_cmp_lt_u32 s2, 64
	s_cbranch_scc0 .LBB0_2711
	s_sub_i32 s3, s3, 0x100
	s_branch .LBB0_2186
.Lssd1_orig:
	s_cmpk_lt_i32 s3, 0x440
	s_cbranch_scc0 .LBB0_2711
